# dil_task: all Q/K/V fragment loads issued up front with SALU task setup; dilated V^T stored group-major so V loads coalesce
# speedup vs baseline: 1.0555x; 1.0269x over previous
.LBB0_658:
	s_barrier
	s_mov_b64 s[10:11], 0x1e00
	v_lshl_add_u64 v[20:21], v[8:9], 0, s[10:11]
	global_load_dwordx4 v[24:27], v[20:21], off offset:0
	global_load_dwordx4 v[28:31], v[20:21], off offset:128
	global_load_dwordx4 v[32:35], v[20:21], off offset:256
	global_load_dwordx4 v[36:39], v[20:21], off offset:384
	global_load_dwordx4 v[40:43], v[20:21], off offset:512
	global_load_dwordx4 v[44:47], v[20:21], off offset:640
	global_load_dwordx4 v[48:51], v[20:21], off offset:768
	global_load_dwordx4 v[52:55], v[20:21], off offset:896
	global_load_dwordx4 v[56:59], v[20:21], off offset:1024
	global_load_dwordx4 v[60:63], v[20:21], off offset:1152
	global_load_dwordx4 v[64:67], v[20:21], off offset:1280
	global_load_dwordx4 v[68:71], v[20:21], off offset:1408
	s_lshr_b32 s4, s28, 3
	s_mul_i32 s5, s28, 0x310
	v_add_u32_e32 v72, s5, v11
	s_and_b32 s10, s4, 1
	s_lshl_b32 s10, s10, 5
	s_lshr_b32 s11, s4, 1
	s_add_i32 s10, s10, s11
	s_mulk_i32 s10, 0x310
	v_add_u32_e32 v73, s10, v11
	s_lshl_b32 s10, s4, 1
	s_mulk_i32 s10, 0x310
	v_add_u32_e32 v74, s10, v11
	v_lshlrev_b32_e32 v75, 3, v6
	s_lshr_b32 s10, s42, 2
	s_lshr_b32 s11, s28, 2
	s_add_i32 s10, s10, s11
	s_lshl_b32 s10, s10, 9
	v_add_u32_e32 v76, s10, v75
	s_lshr_b32 s10, s4, 1
	s_lshl_b32 s10, s10, 10
	s_lshr_b32 s11, s42, 4
	s_add_i32 s10, s10, s11
	s_and_b32 s11, s4, 1
	s_lshl_b32 s11, s11, 1
	s_add_i32 s10, s10, s11
	s_lshl_b32 s10, s10, 9
	v_add_u32_e32 v77, s10, v75
	s_lshl_b32 s10, s4, 9
	s_lshr_b32 s11, s42, 6
	s_add_i32 s10, s10, s11
	s_lshl_b32 s10, s10, 9
	v_add_u32_e32 v78, s10, v75
	v_add_u32_e32 v79, 0x20000, v78
	s_add_u32 s36, s66, 0xd278400
	s_addc_u32 s37, s67, 0
	s_waitcnt vmcnt(6)
	ds_write_b128 v13, v[24:27]
	ds_write_b128 v13, v[28:31] offset:128
	ds_write_b128 v13, v[32:35] offset:256
	ds_write_b128 v13, v[36:39] offset:384
	ds_write_b128 v13, v[40:43] offset:512
	ds_write_b128 v13, v[44:47] offset:640
	s_waitcnt lgkmcnt(0)
	s_barrier
	ds_read_u16 v80, v72 offset:0
	ds_read_u16 v81, v72 offset:784
	ds_read_u16 v82, v72 offset:1568
	ds_read_u16 v83, v72 offset:2352
	ds_read_u16 v84, v72 offset:3136
	ds_read_u16 v85, v72 offset:3920
	ds_read_u16 v86, v72 offset:4704
	ds_read_u16 v87, v72 offset:5488
	ds_read_u16 v88, v72 offset:128
	ds_read_u16 v89, v72 offset:912
	ds_read_u16 v90, v72 offset:1696
	ds_read_u16 v91, v72 offset:2480
	ds_read_u16 v92, v72 offset:3264
	ds_read_u16 v93, v72 offset:4048
	ds_read_u16 v94, v72 offset:4832
	ds_read_u16 v95, v72 offset:5616
	s_waitcnt lgkmcnt(8)
	v_perm_b32 v96, v81, v80, s96
	v_perm_b32 v97, v83, v82, s96
	global_store_dwordx2 v76, v[96:97], s[36:37] offset:0
	v_perm_b32 v98, v85, v84, s96
	v_perm_b32 v99, v87, v86, s96
	global_store_dwordx2 v76, v[98:99], s[36:37] offset:512
	s_add_u32 s36, s36, 0x200000
	s_addc_u32 s37, s37, 0
	ds_read_u16 v80, v72 offset:256
	ds_read_u16 v81, v72 offset:1040
	ds_read_u16 v82, v72 offset:1824
	ds_read_u16 v83, v72 offset:2608
	ds_read_u16 v84, v72 offset:3392
	ds_read_u16 v85, v72 offset:4176
	ds_read_u16 v86, v72 offset:4960
	ds_read_u16 v87, v72 offset:5744
	s_waitcnt lgkmcnt(8)
	v_perm_b32 v100, v89, v88, s96
	v_perm_b32 v101, v91, v90, s96
	global_store_dwordx2 v76, v[100:101], s[36:37] offset:0
	v_perm_b32 v102, v93, v92, s96
	v_perm_b32 v103, v95, v94, s96
	global_store_dwordx2 v76, v[102:103], s[36:37] offset:512
	s_add_u32 s36, s36, 0x200000
	s_addc_u32 s37, s37, 0
	ds_read_u16 v88, v72 offset:384
	ds_read_u16 v89, v72 offset:1168
	ds_read_u16 v90, v72 offset:1952
	ds_read_u16 v91, v72 offset:2736
	ds_read_u16 v92, v72 offset:3520
	ds_read_u16 v93, v72 offset:4304
	ds_read_u16 v94, v72 offset:5088
	ds_read_u16 v95, v72 offset:5872
	s_waitcnt lgkmcnt(8)
	v_perm_b32 v96, v81, v80, s96
	v_perm_b32 v97, v83, v82, s96
	global_store_dwordx2 v76, v[96:97], s[36:37] offset:0
	v_perm_b32 v98, v85, v84, s96
	v_perm_b32 v99, v87, v86, s96
	global_store_dwordx2 v76, v[98:99], s[36:37] offset:512
	s_add_u32 s36, s36, 0x200000
	s_addc_u32 s37, s37, 0
	ds_read_u16 v80, v73 offset:512
	ds_read_u16 v81, v73 offset:3648
	ds_read_u16 v82, v73 offset:6784
	ds_read_u16 v83, v73 offset:9920
	ds_read_u16 v84, v73 offset:13056
	ds_read_u16 v85, v73 offset:16192
	ds_read_u16 v86, v73 offset:19328
	ds_read_u16 v87, v73 offset:22464
	s_waitcnt lgkmcnt(8)
	v_perm_b32 v100, v89, v88, s96
	v_perm_b32 v101, v91, v90, s96
	global_store_dwordx2 v76, v[100:101], s[36:37] offset:0
	v_perm_b32 v102, v93, v92, s96
	v_perm_b32 v103, v95, v94, s96
	global_store_dwordx2 v76, v[102:103], s[36:37] offset:512
	s_add_u32 s36, s36, 0x200000
	s_addc_u32 s37, s37, 0
	ds_read_u16 v88, v73 offset:640
	ds_read_u16 v89, v73 offset:3776
	ds_read_u16 v90, v73 offset:6912
	ds_read_u16 v91, v73 offset:10048
	ds_read_u16 v92, v73 offset:13184
	ds_read_u16 v93, v73 offset:16320
	ds_read_u16 v94, v73 offset:19456
	ds_read_u16 v95, v73 offset:22592
	s_waitcnt lgkmcnt(8)
	v_perm_b32 v96, v81, v80, s96
	v_perm_b32 v97, v83, v82, s96
	global_store_dwordx2 v77, v[96:97], s[36:37] offset:0
	v_perm_b32 v98, v85, v84, s96
	v_perm_b32 v99, v87, v86, s96
	global_store_dwordx2 v77, v[98:99], s[36:37] offset:512
	s_add_u32 s36, s36, 0x200000
	s_addc_u32 s37, s37, 0
	s_waitcnt lgkmcnt(0)
	v_perm_b32 v100, v89, v88, s96
	v_perm_b32 v101, v91, v90, s96
	global_store_dwordx2 v77, v[100:101], s[36:37] offset:0
	v_perm_b32 v102, v93, v92, s96
	v_perm_b32 v103, v95, v94, s96
	global_store_dwordx2 v77, v[102:103], s[36:37] offset:512
	s_add_u32 s36, s36, 0x200000
	s_addc_u32 s37, s37, 0
	s_barrier
	s_waitcnt vmcnt(12)
	ds_write_b128 v13, v[48:51]
	ds_write_b128 v13, v[52:55] offset:128
	ds_write_b128 v13, v[56:59] offset:256
	ds_write_b128 v13, v[60:63] offset:384
	ds_write_b128 v13, v[64:67] offset:512
	ds_write_b128 v13, v[68:71] offset:640
	s_waitcnt lgkmcnt(0)
	s_barrier
	ds_read_u16 v80, v73 offset:0
	ds_read_u16 v81, v73 offset:3136
	ds_read_u16 v82, v73 offset:6272
	ds_read_u16 v83, v73 offset:9408
	ds_read_u16 v84, v73 offset:12544
	ds_read_u16 v85, v73 offset:15680
	ds_read_u16 v86, v73 offset:18816
	ds_read_u16 v87, v73 offset:21952
	ds_read_u16 v88, v73 offset:128
	ds_read_u16 v89, v73 offset:3264
	ds_read_u16 v90, v73 offset:6400
	ds_read_u16 v91, v73 offset:9536
	ds_read_u16 v92, v73 offset:12672
	ds_read_u16 v93, v73 offset:15808
	ds_read_u16 v94, v73 offset:18944
	ds_read_u16 v95, v73 offset:22080
	s_waitcnt lgkmcnt(8)
	v_perm_b32 v96, v81, v80, s96
	v_perm_b32 v97, v83, v82, s96
	global_store_dwordx2 v77, v[96:97], s[36:37] offset:0
	v_perm_b32 v98, v85, v84, s96
	v_perm_b32 v99, v87, v86, s96
	global_store_dwordx2 v77, v[98:99], s[36:37] offset:512
	s_add_u32 s36, s36, 0x200000
	s_addc_u32 s37, s37, 0
	ds_read_u16 v80, v74 offset:256
	ds_read_u16 v81, v74 offset:12800
	ds_read_u16 v82, v74 offset:25344
	ds_read_u16 v83, v74 offset:37888
	ds_read_u16 v84, v74 offset:1040
	ds_read_u16 v85, v74 offset:13584
	ds_read_u16 v86, v74 offset:26128
	ds_read_u16 v87, v74 offset:38672
	s_waitcnt lgkmcnt(8)
	v_perm_b32 v100, v89, v88, s96
	v_perm_b32 v101, v91, v90, s96
	global_store_dwordx2 v77, v[100:101], s[36:37] offset:0
	v_perm_b32 v102, v93, v92, s96
	v_perm_b32 v103, v95, v94, s96
	global_store_dwordx2 v77, v[102:103], s[36:37] offset:512
	s_add_u32 s36, s36, 0x200000
	s_addc_u32 s37, s37, 0
	ds_read_u16 v88, v74 offset:384
	ds_read_u16 v89, v74 offset:12928
	ds_read_u16 v90, v74 offset:25472
	ds_read_u16 v91, v74 offset:38016
	ds_read_u16 v92, v74 offset:1168
	ds_read_u16 v93, v74 offset:13712
	ds_read_u16 v94, v74 offset:26256
	ds_read_u16 v95, v74 offset:38800
	s_waitcnt lgkmcnt(8)
	v_perm_b32 v96, v81, v80, s96
	v_perm_b32 v97, v83, v82, s96
	global_store_dwordx2 v78, v[96:97], s[36:37]
	v_perm_b32 v98, v85, v84, s96
	v_perm_b32 v99, v87, v86, s96
	global_store_dwordx2 v79, v[98:99], s[36:37]
	s_add_u32 s36, s36, 0x200000
	s_addc_u32 s37, s37, 0
	ds_read_u16 v80, v74 offset:512
	ds_read_u16 v81, v74 offset:13056
	ds_read_u16 v82, v74 offset:25600
	ds_read_u16 v83, v74 offset:38144
	ds_read_u16 v84, v74 offset:1296
	ds_read_u16 v85, v74 offset:13840
	ds_read_u16 v86, v74 offset:26384
	ds_read_u16 v87, v74 offset:38928
	s_waitcnt lgkmcnt(8)
	v_perm_b32 v100, v89, v88, s96
	v_perm_b32 v101, v91, v90, s96
	global_store_dwordx2 v78, v[100:101], s[36:37]
	v_perm_b32 v102, v93, v92, s96
	v_perm_b32 v103, v95, v94, s96
	global_store_dwordx2 v79, v[102:103], s[36:37]
	s_add_u32 s36, s36, 0x200000
	s_addc_u32 s37, s37, 0
	ds_read_u16 v88, v74 offset:640
	ds_read_u16 v89, v74 offset:13184
	ds_read_u16 v90, v74 offset:25728
	ds_read_u16 v91, v74 offset:38272
	ds_read_u16 v92, v74 offset:1424
	ds_read_u16 v93, v74 offset:13968
	ds_read_u16 v94, v74 offset:26512
	ds_read_u16 v95, v74 offset:39056
	s_waitcnt lgkmcnt(8)
	v_perm_b32 v96, v81, v80, s96
	v_perm_b32 v97, v83, v82, s96
	global_store_dwordx2 v78, v[96:97], s[36:37]
	v_perm_b32 v98, v85, v84, s96
	v_perm_b32 v99, v87, v86, s96
	global_store_dwordx2 v79, v[98:99], s[36:37]
	s_add_u32 s36, s36, 0x200000
	s_addc_u32 s37, s37, 0
	s_waitcnt lgkmcnt(0)
	v_perm_b32 v100, v89, v88, s96
	v_perm_b32 v101, v91, v90, s96
	global_store_dwordx2 v78, v[100:101], s[36:37]
	v_perm_b32 v102, v93, v92, s96
	v_perm_b32 v103, v95, v94, s96
	global_store_dwordx2 v79, v[102:103], s[36:37]
	s_add_u32 s36, s36, 0x200000
	s_addc_u32 s37, s37, 0
	s_barrier
	s_branch .LBB0_789

.LBB0_1052:
	s_andn2_b64 vcc, exec, s[6:7]
	s_cbranch_vccnz .LBB0_1056
	v_lshl_add_u32 v0, s24, 3, v204
	s_nop 0
	v_readfirstlane_b32 s6, v0
	s_lshr_b32 s7, s6, 10
	s_and_b32 s6, s6, 0x3ff
	s_lshr_b32 s10, s7, 2
	s_lshl_b32 s10, s10, 1
	s_sub_i32 s11, 10, s10
	s_lshr_b32 s12, s6, s11
	s_lshl_b32 s13, s12, s11
	s_sub_i32 s6, s6, s13
	s_lshl_b32 s13, s6, 4
	s_sub_i32 s28, s13, 0x80
	s_lshl_b32 s29, s63, s10
	s_mul_i32 s30, s12, s63
	s_lshl_b32 s31, s7, 7
	s_add_u32 s34, s88, s31
	s_addc_u32 s35, s89, 0
	s_add_u32 s36, s34, 0x1800
	s_addc_u32 s37, s35, 0
	s_lshl_b32 s40, s7, 21
	s_add_u32 s38, s66, 0xd278400
	s_addc_u32 s39, s67, 0
	s_add_u32 s38, s38, s40
	s_addc_u32 s39, s39, 0
	s_lshr_b32 s41, 0x4000, s10
	s_mul_i32 s41, s41, s12
	s_lshl_b32 s41, s41, 7
	s_add_u32 s38, s38, s41
	s_addc_u32 s39, s39, 0
	v_add_u32_e32 v0, s30, v162
	v_add_u32_e32 v114, s28, v205
	v_add_u32_e32 v144, s13, v205
	v_mad_u32_u24 v182, v144, s29, v0
	global_load_dwordx4 v[2:5], v182, s[36:37] offset:-1536
	global_load_dwordx4 v[6:9], v182, s[36:37] offset:-1472
	v_max_i32_e32 v145, 0, v114
	v_mad_u32_u24 v183, v145, s29, v0
	global_load_dwordx4 v[10:13], v183, s[36:37]
	global_load_dwordx4 v[14:17], v183, s[36:37] offset:64
	v_add_u32_e32 v145, 16, v114
	v_max_i32_e32 v145, 0, v145
	v_mad_u32_u24 v184, v145, s29, v0
	global_load_dwordx4 v[18:21], v184, s[36:37]
	global_load_dwordx4 v[22:25], v184, s[36:37] offset:64
	v_add_u32_e32 v145, 32, v114
	v_max_i32_e32 v145, 0, v145
	v_mad_u32_u24 v185, v145, s29, v0
	global_load_dwordx4 v[26:29], v185, s[36:37]
	global_load_dwordx4 v[30:33], v185, s[36:37] offset:64
	v_add_u32_e32 v145, 48, v114
	v_max_i32_e32 v145, 0, v145
	v_mad_u32_u24 v186, v145, s29, v0
	global_load_dwordx4 v[34:37], v186, s[36:37]
	global_load_dwordx4 v[38:41], v186, s[36:37] offset:64
	v_add_u32_e32 v145, 64, v114
	v_max_i32_e32 v145, 0, v145
	v_mad_u32_u24 v187, v145, s29, v0
	global_load_dwordx4 v[42:45], v187, s[36:37]
	global_load_dwordx4 v[46:49], v187, s[36:37] offset:64
	v_add_u32_e32 v145, 0x50, v114
	v_max_i32_e32 v145, 0, v145
	v_mad_u32_u24 v188, v145, s29, v0
	global_load_dwordx4 v[50:53], v188, s[36:37]
	global_load_dwordx4 v[54:57], v188, s[36:37] offset:64
	v_add_u32_e32 v145, 0x60, v114
	v_max_i32_e32 v145, 0, v145
	v_mad_u32_u24 v189, v145, s29, v0
	global_load_dwordx4 v[58:61], v189, s[36:37]
	global_load_dwordx4 v[62:65], v189, s[36:37] offset:64
	v_add_u32_e32 v145, 0x70, v114
	v_max_i32_e32 v145, 0, v145
	v_mad_u32_u24 v190, v145, s29, v0
	global_load_dwordx4 v[66:69], v190, s[36:37]
	global_load_dwordx4 v[70:73], v190, s[36:37] offset:64
	v_add_u32_e32 v145, 0x80, v114
	v_max_i32_e32 v145, 0, v145
	v_mad_u32_u24 v191, v145, s29, v0
	global_load_dwordx4 v[74:77], v191, s[36:37]
	global_load_dwordx4 v[78:81], v191, s[36:37] offset:64
	v_add_u32_e32 v211, s28, v160
	v_lshlrev_b32_e32 v165, 3, v205
	v_max_i32_e32 v145, 0, v211
	v_lshl_add_u32 v236, v145, 7, v165
	v_add_u32_e32 v145, 16, v211
	v_max_i32_e32 v145, 0, v145
	v_lshl_add_u32 v237, v145, 7, v165
	global_load_dwordx2 v[82:83], v236, s[38:39]
	global_load_dwordx2 v[84:85], v237, s[38:39]
	global_load_dwordx2 v[86:87], v236, s[38:39] offset:128
	global_load_dwordx2 v[88:89], v237, s[38:39] offset:128
	global_load_dwordx2 v[90:91], v236, s[38:39] offset:256
	global_load_dwordx2 v[92:93], v237, s[38:39] offset:256
	global_load_dwordx2 v[94:95], v236, s[38:39] offset:384
	global_load_dwordx2 v[96:97], v237, s[38:39] offset:384
	v_add_u32_e32 v145, 32, v211
	v_max_i32_e32 v145, 0, v145
	v_lshl_add_u32 v238, v145, 7, v165
	v_add_u32_e32 v145, 48, v211
	v_max_i32_e32 v145, 0, v145
	v_lshl_add_u32 v239, v145, 7, v165
	global_load_dwordx2 v[98:99], v238, s[38:39]
	global_load_dwordx2 v[100:101], v239, s[38:39]
	global_load_dwordx2 v[102:103], v238, s[38:39] offset:128
	global_load_dwordx2 v[104:105], v239, s[38:39] offset:128
	global_load_dwordx2 v[106:107], v238, s[38:39] offset:256
	global_load_dwordx2 v[108:109], v239, s[38:39] offset:256
	global_load_dwordx2 v[110:111], v238, s[38:39] offset:384
	global_load_dwordx2 v[112:113], v239, s[38:39] offset:384
	v_add_u32_e32 v145, 64, v211
	v_max_i32_e32 v145, 0, v145
	v_lshl_add_u32 v240, v145, 7, v165
	v_add_u32_e32 v145, 0x50, v211
	v_max_i32_e32 v145, 0, v145
	v_lshl_add_u32 v241, v145, 7, v165
	global_load_dwordx2 v[116:117], v240, s[38:39]
	global_load_dwordx2 v[118:119], v241, s[38:39]
	global_load_dwordx2 v[120:121], v240, s[38:39] offset:128
	global_load_dwordx2 v[122:123], v241, s[38:39] offset:128
	global_load_dwordx2 v[124:125], v240, s[38:39] offset:256
	global_load_dwordx2 v[126:127], v241, s[38:39] offset:256
	global_load_dwordx2 v[128:129], v240, s[38:39] offset:384
	global_load_dwordx2 v[130:131], v241, s[38:39] offset:384
	v_add_u32_e32 v145, 0x60, v211
	v_max_i32_e32 v145, 0, v145
	v_lshl_add_u32 v242, v145, 7, v165
	v_add_u32_e32 v145, 0x70, v211
	v_max_i32_e32 v145, 0, v145
	v_lshl_add_u32 v243, v145, 7, v165
	global_load_dwordx2 v[132:133], v242, s[38:39]
	global_load_dwordx2 v[134:135], v243, s[38:39]
	global_load_dwordx2 v[136:137], v242, s[38:39] offset:128
	global_load_dwordx2 v[138:139], v243, s[38:39] offset:128
	global_load_dwordx2 v[140:141], v242, s[38:39] offset:256
	global_load_dwordx2 v[142:143], v243, s[38:39] offset:256
	global_load_dwordx2 v[166:167], v242, s[38:39] offset:384
	global_load_dwordx2 v[168:169], v243, s[38:39] offset:384
	v_add_u32_e32 v145, 0x80, v211
	v_max_i32_e32 v145, 0, v145
	v_lshl_add_u32 v244, v145, 7, v165
	global_load_dwordx2 v[170:171], v244, s[38:39]
	v_mov_b32_e32 v172, 0
	v_mov_b32_e32 v173, 0
	global_load_dwordx2 v[174:175], v244, s[38:39] offset:128
	v_mov_b32_e32 v176, 0
	v_mov_b32_e32 v177, 0
	global_load_dwordx2 v[212:213], v244, s[38:39] offset:256
	v_mov_b32_e32 v214, 0
	v_mov_b32_e32 v215, 0
	global_load_dwordx2 v[216:217], v244, s[38:39] offset:384
	v_mov_b32_e32 v218, 0
	v_mov_b32_e32 v219, 0
	v_sub_u32_e32 v178, v205, v160
	v_cmp_ge_i32_e64 s[42:43], 0, v178
	v_cmp_ge_i32_e64 s[44:45], 1, v178
	v_cmp_ge_i32_e64 s[46:47], 2, v178
	v_cmp_ge_i32_e64 s[48:49], 3, v178
	s_waitcnt vmcnt(53)
	v_mfma_f32_16x16x32_bf16 v[10:13], v[10:13], v[2:5], 0
	s_waitcnt vmcnt(52)
	v_mfma_f32_16x16x32_bf16 v[10:13], v[14:17], v[6:9], v[10:13]
	s_waitcnt vmcnt(51)
	v_mfma_f32_16x16x32_bf16 v[18:21], v[18:21], v[2:5], 0
	s_waitcnt vmcnt(50)
	v_mfma_f32_16x16x32_bf16 v[18:21], v[22:25], v[6:9], v[18:21]
	s_waitcnt vmcnt(49)
	v_mfma_f32_16x16x32_bf16 v[26:29], v[26:29], v[2:5], 0
	s_waitcnt vmcnt(48)
	v_mfma_f32_16x16x32_bf16 v[26:29], v[30:33], v[6:9], v[26:29]
	s_waitcnt vmcnt(47)
	v_mfma_f32_16x16x32_bf16 v[34:37], v[34:37], v[2:5], 0
	s_waitcnt vmcnt(46)
	v_mfma_f32_16x16x32_bf16 v[34:37], v[38:41], v[6:9], v[34:37]
	s_waitcnt vmcnt(45)
	v_mfma_f32_16x16x32_bf16 v[42:45], v[42:45], v[2:5], 0
	s_waitcnt vmcnt(44)
	v_mfma_f32_16x16x32_bf16 v[42:45], v[46:49], v[6:9], v[42:45]
	s_waitcnt vmcnt(43)
	v_mfma_f32_16x16x32_bf16 v[50:53], v[50:53], v[2:5], 0
	s_waitcnt vmcnt(42)
	v_mfma_f32_16x16x32_bf16 v[50:53], v[54:57], v[6:9], v[50:53]
	s_waitcnt vmcnt(41)
	v_mfma_f32_16x16x32_bf16 v[58:61], v[58:61], v[2:5], 0
	s_waitcnt vmcnt(40)
	v_mfma_f32_16x16x32_bf16 v[58:61], v[62:65], v[6:9], v[58:61]
	s_waitcnt vmcnt(39)
	v_mfma_f32_16x16x32_bf16 v[66:69], v[66:69], v[2:5], 0
	s_waitcnt vmcnt(38)
	v_mfma_f32_16x16x32_bf16 v[66:69], v[70:73], v[6:9], v[66:69]
	s_waitcnt vmcnt(37)
	v_mfma_f32_16x16x32_bf16 v[74:77], v[74:77], v[2:5], 0
	s_waitcnt vmcnt(36)
	v_mfma_f32_16x16x32_bf16 v[74:77], v[78:81], v[6:9], v[74:77]
	s_cmp_ge_i32 s6, 8
	s_cbranch_scc1 .Ldil_m_fast
	v_mov_b32_e32 v10, v201
	v_mov_b32_e32 v11, v201
	v_mov_b32_e32 v12, v201
	v_mov_b32_e32 v13, v201
	s_cmp_ge_i32 s6, 7
	s_cselect_b64 vcc, -1, 0
	v_cndmask_b32_e32 v18, v201, v18, vcc
	v_cndmask_b32_e32 v19, v201, v19, vcc
	v_cndmask_b32_e32 v20, v201, v20, vcc
	v_cndmask_b32_e32 v21, v201, v21, vcc
	s_cmp_ge_i32 s6, 6
	s_cselect_b64 vcc, -1, 0
	v_cndmask_b32_e32 v26, v201, v26, vcc
	v_cndmask_b32_e32 v27, v201, v27, vcc
	v_cndmask_b32_e32 v28, v201, v28, vcc
	v_cndmask_b32_e32 v29, v201, v29, vcc
	s_cmp_ge_i32 s6, 5
	s_cselect_b64 vcc, -1, 0
	v_cndmask_b32_e32 v34, v201, v34, vcc
	v_cndmask_b32_e32 v35, v201, v35, vcc
	v_cndmask_b32_e32 v36, v201, v36, vcc
	v_cndmask_b32_e32 v37, v201, v37, vcc
	s_cmp_ge_i32 s6, 4
	s_cselect_b64 vcc, -1, 0
	v_cndmask_b32_e32 v42, v201, v42, vcc
	v_cndmask_b32_e32 v43, v201, v43, vcc
	v_cndmask_b32_e32 v44, v201, v44, vcc
	v_cndmask_b32_e32 v45, v201, v45, vcc
	s_cmp_ge_i32 s6, 3
	s_cselect_b64 vcc, -1, 0
	v_cndmask_b32_e32 v50, v201, v50, vcc
	v_cndmask_b32_e32 v51, v201, v51, vcc
	v_cndmask_b32_e32 v52, v201, v52, vcc
	v_cndmask_b32_e32 v53, v201, v53, vcc
	s_cmp_ge_i32 s6, 2
	s_cselect_b64 vcc, -1, 0
	v_cndmask_b32_e32 v58, v201, v58, vcc
	v_cndmask_b32_e32 v59, v201, v59, vcc
	v_cndmask_b32_e32 v60, v201, v60, vcc
	v_cndmask_b32_e32 v61, v201, v61, vcc
	s_cmp_ge_i32 s6, 1
	s_cselect_b64 vcc, -1, 0
	v_cndmask_b32_e32 v66, v201, v66, vcc
	v_cndmask_b32_e32 v67, v201, v67, vcc
	v_cndmask_b32_e32 v68, v201, v68, vcc
	v_cndmask_b32_e32 v69, v201, v69, vcc
	s_branch .Ldil_m_join
.Ldil_m_fast:
	v_cndmask_b32_e64 v10, v201, v10, s[42:43]
	v_cndmask_b32_e64 v11, v201, v11, s[44:45]
	v_cndmask_b32_e64 v12, v201, v12, s[46:47]
	v_cndmask_b32_e64 v13, v201, v13, s[48:49]
.Ldil_m_join:
	v_cmp_le_i32_e64 s[42:43], 0, v178
	v_cmp_le_i32_e64 s[44:45], 1, v178
	v_cmp_le_i32_e64 s[46:47], 2, v178
	v_cmp_le_i32_e64 s[48:49], 3, v178
	v_max3_f32 v179, v10, v11, v12
	v_max3_f32 v179, v179, v13, v18
	v_max3_f32 v179, v179, v19, v20
	v_max3_f32 v179, v179, v21, v26
	v_max3_f32 v179, v179, v27, v28
	v_max3_f32 v179, v179, v29, v34
	v_max3_f32 v179, v179, v35, v36
	v_max3_f32 v179, v179, v37, v42
	v_max3_f32 v179, v179, v43, v44
	v_max3_f32 v179, v179, v45, v50
	v_max3_f32 v179, v179, v51, v52
	v_max3_f32 v179, v179, v53, v58
	v_max3_f32 v179, v179, v59, v60
	v_max3_f32 v179, v179, v61, v66
	v_max3_f32 v179, v179, v67, v68
	v_max_f32_e32 v179, v179, v69
	v_cndmask_b32_e64 v74, v201, v74, s[42:43]
	v_cndmask_b32_e64 v75, v201, v75, s[44:45]
	v_cndmask_b32_e64 v76, v201, v76, s[46:47]
	v_cndmask_b32_e64 v77, v201, v77, s[48:49]
	v_max3_f32 v179, v179, v74, v75
	v_max3_f32 v179, v179, v76, v77
	v_mov_b32_e32 v180, v179
	s_nop 1
	v_permlane16_swap_b32_e32 v179, v180
	v_max_f32_e32 v180, v180, v180
	v_max_f32_e32 v179, v179, v179
	v_max_f32_e32 v179, v179, v180
	v_mov_b32_e32 v180, v179
	s_nop 1
	v_permlane32_swap_b32_e32 v179, v180
	v_max_f32_e32 v180, v180, v180
	v_max_f32_e32 v179, v179, v179
	v_max_f32_e32 v179, v179, v180
	v_sub_f32_e32 v145, v10, v179
	v_exp_f32_e32 v10, v145
	v_sub_f32_e32 v114, v11, v179
	v_exp_f32_e32 v11, v114
	v_sub_f32_e32 v145, v12, v179
	v_exp_f32_e32 v12, v145
	v_add_f32_e32 v163, v11, v10
	v_sub_f32_e32 v114, v13, v179
	v_exp_f32_e32 v13, v114
	v_add_f32_e32 v163, v12, v163
	v_sub_f32_e32 v145, v18, v179
	v_exp_f32_e32 v18, v145
	v_add_f32_e32 v163, v13, v163
	v_sub_f32_e32 v114, v19, v179
	v_exp_f32_e32 v19, v114
	v_add_f32_e32 v163, v18, v163
	v_sub_f32_e32 v145, v20, v179
	v_exp_f32_e32 v20, v145
	v_add_f32_e32 v163, v19, v163
	v_sub_f32_e32 v114, v21, v179
	v_exp_f32_e32 v21, v114
	v_add_f32_e32 v163, v20, v163
	v_sub_f32_e32 v145, v26, v179
	v_exp_f32_e32 v26, v145
	v_add_f32_e32 v163, v21, v163
	v_sub_f32_e32 v114, v27, v179
	v_exp_f32_e32 v27, v114
	v_add_f32_e32 v163, v26, v163
	v_sub_f32_e32 v145, v28, v179
	v_exp_f32_e32 v28, v145
	v_add_f32_e32 v163, v27, v163
	v_sub_f32_e32 v114, v29, v179
	v_exp_f32_e32 v29, v114
	v_add_f32_e32 v163, v28, v163
	v_sub_f32_e32 v145, v34, v179
	v_exp_f32_e32 v34, v145
	v_add_f32_e32 v163, v29, v163
	v_sub_f32_e32 v114, v35, v179
	v_exp_f32_e32 v35, v114
	v_add_f32_e32 v163, v34, v163
	v_sub_f32_e32 v145, v36, v179
	v_exp_f32_e32 v36, v145
	v_add_f32_e32 v163, v35, v163
	v_sub_f32_e32 v114, v37, v179
	v_exp_f32_e32 v37, v114
	v_add_f32_e32 v163, v36, v163
	v_sub_f32_e32 v145, v42, v179
	v_exp_f32_e32 v42, v145
	v_add_f32_e32 v163, v37, v163
	v_sub_f32_e32 v114, v43, v179
	v_exp_f32_e32 v43, v114
	v_add_f32_e32 v163, v42, v163
	v_sub_f32_e32 v145, v44, v179
	v_exp_f32_e32 v44, v145
	v_add_f32_e32 v163, v43, v163
	v_sub_f32_e32 v114, v45, v179
	v_exp_f32_e32 v45, v114
	v_add_f32_e32 v163, v44, v163
	v_sub_f32_e32 v145, v50, v179
	v_exp_f32_e32 v50, v145
	v_add_f32_e32 v163, v45, v163
	v_sub_f32_e32 v114, v51, v179
	v_exp_f32_e32 v51, v114
	v_add_f32_e32 v163, v50, v163
	v_sub_f32_e32 v145, v52, v179
	v_exp_f32_e32 v52, v145
	v_add_f32_e32 v163, v51, v163
	v_sub_f32_e32 v114, v53, v179
	v_exp_f32_e32 v53, v114
	v_add_f32_e32 v163, v52, v163
	v_sub_f32_e32 v145, v58, v179
	v_exp_f32_e32 v58, v145
	v_add_f32_e32 v163, v53, v163
	v_sub_f32_e32 v114, v59, v179
	v_exp_f32_e32 v59, v114
	v_add_f32_e32 v163, v58, v163
	v_sub_f32_e32 v145, v60, v179
	v_exp_f32_e32 v60, v145
	v_add_f32_e32 v163, v59, v163
	v_sub_f32_e32 v114, v61, v179
	v_exp_f32_e32 v61, v114
	v_add_f32_e32 v163, v60, v163
	v_sub_f32_e32 v145, v66, v179
	v_exp_f32_e32 v66, v145
	v_add_f32_e32 v163, v61, v163
	v_sub_f32_e32 v114, v67, v179
	v_exp_f32_e32 v67, v114
	v_add_f32_e32 v163, v66, v163
	v_sub_f32_e32 v145, v68, v179
	v_exp_f32_e32 v68, v145
	v_add_f32_e32 v163, v67, v163
	v_sub_f32_e32 v114, v69, v179
	v_exp_f32_e32 v69, v114
	v_add_f32_e32 v163, v68, v163
	v_sub_f32_e32 v145, v74, v179
	v_exp_f32_e32 v74, v145
	v_add_f32_e32 v163, v69, v163
	v_sub_f32_e32 v114, v75, v179
	v_exp_f32_e32 v75, v114
	v_add_f32_e32 v163, v74, v163
	v_sub_f32_e32 v145, v76, v179
	v_exp_f32_e32 v76, v145
	v_add_f32_e32 v163, v75, v163
	v_sub_f32_e32 v114, v77, v179
	v_exp_f32_e32 v77, v114
	v_add_f32_e32 v163, v76, v163
	s_nop 0
	v_add_f32_e32 v163, v77, v163
	v_mov_b32_e32 v180, v163
	s_nop 1
	v_permlane16_swap_b32_e32 v163, v180
	v_add_f32_e32 v163, v163, v180
	v_mov_b32_e32 v180, v163
	s_nop 1
	v_permlane32_swap_b32_e32 v163, v180
	v_add_f32_e32 v163, v163, v180
	v_cvt_pk_bf16_f32 v14, v10, v11
	v_cvt_pk_bf16_f32 v15, v12, v13
	v_cvt_pk_bf16_f32 v16, v18, v19
	v_cvt_pk_bf16_f32 v17, v20, v21
	v_cvt_pk_bf16_f32 v22, v26, v27
	v_cvt_pk_bf16_f32 v23, v28, v29
	v_cvt_pk_bf16_f32 v24, v34, v35
	v_cvt_pk_bf16_f32 v25, v36, v37
	v_cvt_pk_bf16_f32 v30, v42, v43
	v_cvt_pk_bf16_f32 v31, v44, v45
	v_cvt_pk_bf16_f32 v32, v50, v51
	v_cvt_pk_bf16_f32 v33, v52, v53
	v_cvt_pk_bf16_f32 v38, v58, v59
	v_cvt_pk_bf16_f32 v39, v60, v61
	v_cvt_pk_bf16_f32 v40, v66, v67
	v_cvt_pk_bf16_f32 v41, v68, v69
	v_cvt_pk_bf16_f32 v46, v74, v75
	v_cvt_pk_bf16_f32 v47, v76, v77
	v_mov_b32_e32 v48, 0
	v_mov_b32_e32 v49, 0
	v_lshlrev_b32_e32 v144, s10, v144
	v_add_u32_e32 v144, s12, v144
	s_waitcnt vmcnt(34)
	v_mfma_f32_16x16x32_bf16 v[220:223], v[82:85], v[14:17], 0
	s_waitcnt vmcnt(32)
	v_mfma_f32_16x16x32_bf16 v[224:227], v[86:89], v[14:17], 0
	s_waitcnt vmcnt(30)
	v_mfma_f32_16x16x32_bf16 v[228:231], v[90:93], v[14:17], 0
	s_waitcnt vmcnt(28)
	v_mfma_f32_16x16x32_bf16 v[232:235], v[94:97], v[14:17], 0
	s_waitcnt vmcnt(26)
	v_mfma_f32_16x16x32_bf16 v[220:223], v[98:101], v[22:25], v[220:223]
	s_waitcnt vmcnt(24)
	v_mfma_f32_16x16x32_bf16 v[224:227], v[102:105], v[22:25], v[224:227]
	s_waitcnt vmcnt(22)
	v_mfma_f32_16x16x32_bf16 v[228:231], v[106:109], v[22:25], v[228:231]
	s_waitcnt vmcnt(20)
	v_mfma_f32_16x16x32_bf16 v[232:235], v[110:113], v[22:25], v[232:235]
	s_waitcnt vmcnt(18)
	v_mfma_f32_16x16x32_bf16 v[220:223], v[116:119], v[30:33], v[220:223]
	s_waitcnt vmcnt(16)
	v_mfma_f32_16x16x32_bf16 v[224:227], v[120:123], v[30:33], v[224:227]
	s_waitcnt vmcnt(14)
	v_mfma_f32_16x16x32_bf16 v[228:231], v[124:127], v[30:33], v[228:231]
	s_waitcnt vmcnt(12)
	v_mfma_f32_16x16x32_bf16 v[232:235], v[128:131], v[30:33], v[232:235]
	s_waitcnt vmcnt(10)
	v_mfma_f32_16x16x32_bf16 v[220:223], v[132:135], v[38:41], v[220:223]
	s_waitcnt vmcnt(8)
	v_mfma_f32_16x16x32_bf16 v[224:227], v[136:139], v[38:41], v[224:227]
	s_waitcnt vmcnt(6)
	v_mfma_f32_16x16x32_bf16 v[228:231], v[140:143], v[38:41], v[228:231]
	s_waitcnt vmcnt(4)
	v_mfma_f32_16x16x32_bf16 v[232:235], v[166:169], v[38:41], v[232:235]
	s_waitcnt vmcnt(3)
	v_mfma_f32_16x16x32_bf16 v[220:223], v[170:173], v[46:49], v[220:223]
	s_waitcnt vmcnt(2)
	v_mfma_f32_16x16x32_bf16 v[224:227], v[174:177], v[46:49], v[224:227]
	s_waitcnt vmcnt(1)
	v_mfma_f32_16x16x32_bf16 v[228:231], v[212:215], v[46:49], v[228:231]
	s_waitcnt vmcnt(0)
	v_mfma_f32_16x16x32_bf16 v[232:235], v[216:219], v[46:49], v[232:235]
	v_div_scale_f32 v0, s[46:47], v163, v163, 1.0
	v_rcp_f32_e32 v6, v0
	s_nop 0
	v_fma_f32 v7, -v0, v6, 1.0
	v_fmac_f32_e32 v6, v7, v6
	v_div_scale_f32 v7, vcc, 1.0, v163, 1.0
	v_mul_f32_e32 v8, v7, v6
	v_fma_f32 v9, -v0, v8, v7
	v_fmac_f32_e32 v8, v9, v6
	v_fma_f32 v0, -v0, v8, v7
	v_div_fmas_f32 v0, v0, v6, v8
	v_div_fixup_f32 v6, v0, v163, 1.0
	v_lshlrev_b32_e32 v0, 1, v160
	v_sub_u32_e32 v0, v182, v0
	v_pk_mul_f32 v[220:221], v[6:7], v[220:221] op_sel_hi:[0,1]
	v_pk_mul_f32 v[222:223], v[6:7], v[222:223] op_sel_hi:[0,1]
	v_cvt_pk_bf16_f32 v10, v220, v221
	v_cvt_pk_bf16_f32 v11, v222, v223
	global_store_dwordx2 v0, v[10:11], s[34:35]
	v_pk_mul_f32 v[224:225], v[6:7], v[224:225] op_sel_hi:[0,1]
	v_pk_mul_f32 v[226:227], v[6:7], v[226:227] op_sel_hi:[0,1]
	v_cvt_pk_bf16_f32 v12, v224, v225
	v_cvt_pk_bf16_f32 v13, v226, v227
	global_store_dwordx2 v0, v[12:13], s[34:35] offset:32
	v_pk_mul_f32 v[228:229], v[6:7], v[228:229] op_sel_hi:[0,1]
	v_pk_mul_f32 v[230:231], v[6:7], v[230:231] op_sel_hi:[0,1]
	v_cvt_pk_bf16_f32 v14, v228, v229
	v_cvt_pk_bf16_f32 v15, v230, v231
	global_store_dwordx2 v0, v[14:15], s[34:35] offset:64
	v_pk_mul_f32 v[232:233], v[6:7], v[232:233] op_sel_hi:[0,1]
	v_pk_mul_f32 v[234:235], v[6:7], v[234:235] op_sel_hi:[0,1]
	v_cvt_pk_bf16_f32 v16, v232, v233
	v_cvt_pk_bf16_f32 v17, v234, v235
	global_store_dwordx2 v0, v[16:17], s[34:35] offset:96
	v_log_f32_e32 v2, v163
	s_lshl_b32 s31, s7, 16
	s_add_u32 s40, s66, 0x108400
	s_addc_u32 s41, s67, 0
	s_add_u32 s40, s40, s31
	s_addc_u32 s41, s41, 0
	v_lshlrev_b32_e32 v144, 2, v144
	v_add_f32_e32 v2, v179, v2
	s_mov_b64 s[28:29], exec
	s_and_b64 exec, exec, 0xffff
	global_store_dword v144, v2, s[40:41]
